# prompt loops: stagger sleep 18 (was 12) for waves 0-3 together with the static priority for waves 4-7
# speedup vs baseline: 1.0018x; 1.0018x over previous
; template <int MODE, bool SAMPLE>
; __device__ __forceinline__ void attn_unit(const Params& p, char* lds, int b, int h, int qb) {
;     ...
;         if (j > jfirst) continue;
;         const int buf = par;
;         WRITET(buf, stg2[NS == 2 ? par : 0]);
;         if (j >= NS) LOADT(j - NS, stg2[NS == 2 ? par : 0]);
;         __syncthreads();
;         if (wact && j <= jd && var < 2) {
.LBB0_685:
	s_cmp_ge_i32 s20, s13
	s_waitcnt lgkmcnt(0)
	s_barrier
	s_cbranch_scc1 .LBB0_693
	v_readfirstlane_b32 s98, v183
	s_cmpk_ge_u32 s98, 0x100
	s_cbranch_scc1 .Lstg_0
	s_sleep 18

; template <int MODE, bool SAMPLE>
; __device__ __forceinline__ void attn_unit(const Params& p, char* lds, int b, int h, int qb) {
;     ...
;         if (j > jfirst) continue;
;         const int buf = par;
;         WRITET(buf, stg2[NS == 2 ? par : 0]);
;         if (j >= NS) LOADT(j - NS, stg2[NS == 2 ? par : 0]);
;         __syncthreads();
;         if (wact && j <= jd && var < 2) {
.LBB0_696:
	s_cmp_gt_i32 s20, s13
	s_waitcnt lgkmcnt(0)
	s_barrier
	s_cbranch_scc1 .LBB0_681
	v_readfirstlane_b32 s98, v183
	s_cmpk_ge_u32 s98, 0x100
	s_cbranch_scc1 .Lstg_1
	s_sleep 18

; template <int MODE, bool SAMPLE>
; __device__ __forceinline__ void attn_unit(const Params& p, char* lds, int b, int h, int qb) {
;     ...
;         if (j > jfirst) continue;
;         const int buf = par;
;         WRITET(buf, stg2[NS == 2 ? par : 0]);
;         if (j >= NS) LOADT(j - NS, stg2[NS == 2 ? par : 0]);
;         __syncthreads();
;         if (wact && j <= jd && var < 2) {
.LBB0_711:
	s_cmp_ge_u32 s33, s13
	s_waitcnt lgkmcnt(0)
	s_barrier
	s_cbranch_scc1 .LBB0_715
	v_readfirstlane_b32 s98, v183
	s_cmpk_ge_u32 s98, 0x100
	s_cbranch_scc1 .Lstg_2
	s_sleep 18

; template <int MODE, bool SAMPLE>
; __device__ __forceinline__ void attn_unit(const Params& p, char* lds, int b, int h, int qb) {
;     ...
;         if (j > jfirst) continue;
;         const int buf = par;
;         WRITET(buf, stg2[NS == 2 ? par : 0]);
;         if (j >= NS) LOADT(j - NS, stg2[NS == 2 ? par : 0]);
;         __syncthreads();
;         if (wact && j <= jd && var < 2) {
.LBB0_718:
	s_cmp_gt_u32 s33, s13
	s_waitcnt lgkmcnt(0)
	s_barrier
	s_cbranch_scc1 .LBB0_707
	v_readfirstlane_b32 s98, v183
	s_cmpk_ge_u32 s98, 0x100
	s_cbranch_scc1 .Lstg_3
	s_sleep 18

; template <int MODE, bool SAMPLE>
; __device__ __forceinline__ void attn_unit(const Params& p, char* lds, int b, int h, int qb) {
;     ...
;         if (j > jfirst) continue;
;         const int buf = par;
;         WRITET(buf, stg2[NS == 2 ? par : 0]);
;         if (j >= NS) LOADT(j - NS, stg2[NS == 2 ? par : 0]);
;         __syncthreads();
;         if (wact && j <= jd && var < 2) {
.LBB0_760:
	s_cmp_ge_i32 s18, s11
	s_waitcnt lgkmcnt(0)
	s_barrier
	s_cbranch_scc1 .LBB0_768
	v_readfirstlane_b32 s98, v183
	s_cmpk_ge_u32 s98, 0x100
	s_cbranch_scc1 .Lstg_4
	s_sleep 18

; template <int MODE, bool SAMPLE>
; __device__ __forceinline__ void attn_unit(const Params& p, char* lds, int b, int h, int qb) {
;     ...
;         if (j > jfirst) continue;
;         const int buf = par;
;         WRITET(buf, stg2[NS == 2 ? par : 0]);
;         if (j >= NS) LOADT(j - NS, stg2[NS == 2 ? par : 0]);
;         __syncthreads();
;         if (wact && j <= jd && var < 2) {
.LBB0_771:
	s_cmp_gt_i32 s18, s11
	s_waitcnt lgkmcnt(0)
	s_barrier
	s_cbranch_scc1 .LBB0_756
	v_readfirstlane_b32 s98, v183
	s_cmpk_ge_u32 s98, 0x100
	s_cbranch_scc1 .Lstg_5
	s_sleep 18

; template <int MODE, bool SAMPLE>
; __device__ __forceinline__ void attn_unit(const Params& p, char* lds, int b, int h, int qb) {
;     ...
;         if (j > jfirst) continue;
;         const int buf = par;
;         WRITET(buf, stg2[NS == 2 ? par : 0]);
;         if (j >= NS) LOADT(j - NS, stg2[NS == 2 ? par : 0]);
;         __syncthreads();
;         if (wact && j <= jd && var < 2) {
.LBB0_786:
	s_cmp_ge_u32 s33, s11
	s_waitcnt lgkmcnt(0)
	s_barrier
	s_cbranch_scc1 .LBB0_790
	v_readfirstlane_b32 s98, v183
	s_cmpk_ge_u32 s98, 0x100
	s_cbranch_scc1 .Lstg_6
	s_sleep 18

; template <int MODE, bool SAMPLE>
; __device__ __forceinline__ void attn_unit(const Params& p, char* lds, int b, int h, int qb) {
;     ...
;         if (j > jfirst) continue;
;         const int buf = par;
;         WRITET(buf, stg2[NS == 2 ? par : 0]);
;         if (j >= NS) LOADT(j - NS, stg2[NS == 2 ? par : 0]);
;         __syncthreads();
;         if (wact && j <= jd && var < 2) {
.LBB0_793:
	s_cmp_gt_u32 s33, s11
	s_waitcnt lgkmcnt(0)
	s_barrier
	s_cbranch_scc1 .LBB0_782
	v_readfirstlane_b32 s98, v183
	s_cmpk_ge_u32 s98, 0x100
	s_cbranch_scc1 .Lstg_7
	s_sleep 18
